# attention output stores staged through a per-wave LDS tile and written as full-row 16-byte stores (coalesced), on top of the conversion rewrite
# baseline (speedup 1.0000x reference)
.LBB0_347:
	v_cndmask_b32_e64 v72, v48, v212, s[2:3]
	v_cndmask_b32_e64 v167, v72, v48, s[4:5]
	v_max3_f32 v48, v98, s64, v105
	v_max3_f32 v48, v48, v104, v103
	v_max3_f32 v48, v48, v102, v101
	v_max3_f32 v48, v48, v100, v99
	v_max3_f32 v48, v48, v71, v70
	v_max3_f32 v48, v48, v69, v68
	v_max3_f32 v48, v48, v67, v66
	v_max3_f32 v48, v48, v65, v64
	v_max3_f32 v48, v48, v32, v33
	v_max3_f32 v48, v48, v34, v35
	v_max3_f32 v48, v48, v36, v37
	v_max3_f32 v48, v48, v38, v39
	v_max3_f32 v48, v48, v40, v41
	v_max3_f32 v48, v48, v42, v43
	v_max3_f32 v48, v48, v44, v45
	v_max3_f32 v48, v48, v46, v47
	v_max3_f32 v48, v48, v16, v17
	v_max3_f32 v48, v48, v18, v19
	v_max3_f32 v48, v48, v20, v21
	v_max3_f32 v48, v48, v22, v23
	v_max3_f32 v48, v48, v24, v25
	v_max3_f32 v48, v48, v26, v27
	v_max3_f32 v48, v48, v28, v29
	v_max3_f32 v48, v48, v30, v31
	v_max3_f32 v48, v48, v0, v1
	v_max3_f32 v48, v48, v2, v3
	v_max3_f32 v48, v48, v4, v5
	v_max3_f32 v48, v48, v6, v7
	v_max3_f32 v48, v48, v8, v9
	v_max3_f32 v48, v48, v10, v11
	v_max3_f32 v48, v48, v12, v13
	v_cndmask_b32_e64 v166, v212, v49, s[4:5]
	v_max3_f32 v48, v48, v14, v15
	v_cndmask_b32_e64 v168, v50, v212, s[6:7]
	v_cndmask_b32_e64 v169, v51, v212, s[8:9]
	v_max3_f32 v48, v48, v167, v166
	v_cndmask_b32_e64 v170, v52, v212, s[10:11]
	v_cndmask_b32_e64 v171, v53, v212, s[12:13]
	v_max3_f32 v48, v48, v168, v169
	v_cndmask_b32_e64 v172, v54, v212, s[14:15]
	v_cndmask_b32_e64 v173, v55, v212, s[16:17]
	v_max3_f32 v48, v48, v170, v171
	v_cndmask_b32_e64 v174, v56, v212, s[18:19]
	v_cndmask_b32_e64 v175, v57, v212, s[20:21]
	v_max3_f32 v48, v48, v172, v173
	v_cndmask_b32_e64 v176, v58, v212, s[22:23]
	v_cndmask_b32_e64 v177, v59, v212, s[24:25]
	v_max3_f32 v48, v48, v174, v175
	v_cndmask_b32_e64 v178, v60, v212, s[26:27]
	v_cndmask_b32_e64 v179, v61, v212, s[28:29]
	v_max3_f32 v48, v48, v176, v177
	v_cndmask_b32_e64 v180, v62, v212, s[30:31]
	v_cndmask_b32_e64 v181, v63, v212, s[34:35]
	v_max3_f32 v48, v48, v178, v179
	v_max3_f32 v48, v48, v180, v181
	ds_bpermute_b32 v49, v188, v48
	v_or_b32_e32 v153, s89, v118
	v_readlane_b32 s0, v255, 16
	s_add_i32 s96, s96, s1
	s_add_i32 s90, s90, s0
	s_waitcnt lgkmcnt(0)
	v_max3_f32 v213, v48, v49, v96
	v_sub_f32_e32 v50, v104, v213
	v_exp_f32_e32 v154, v50
	v_sub_f32_e32 v50, v103, v213
	v_exp_f32_e32 v155, v50
	v_sub_f32_e32 v50, v102, v213
	v_exp_f32_e32 v160, v50
	v_sub_f32_e32 v50, v101, v213
	v_exp_f32_e32 v161, v50
	v_sub_f32_e32 v50, v100, v213
	v_sub_f32_e32 v48, v98, v213
	v_exp_f32_e32 v164, v50
	v_sub_f32_e32 v50, v99, v213
	v_exp_f32_e32 v110, v48
	v_sub_f32_e32 v48, v105, v213
	v_exp_f32_e32 v165, v50
	v_sub_f32_e32 v50, v71, v213
	v_exp_f32_e32 v111, v48
	v_exp_f32_e32 v102, v50
	v_sub_f32_e32 v50, v70, v213
	v_exp_f32_e32 v103, v50
	v_sub_f32_e32 v50, v69, v213
	v_sub_f32_e32 v34, v34, v213
	v_exp_f32_e32 v112, v50
	v_sub_f32_e32 v50, v68, v213
	v_exp_f32_e32 v106, v34
	v_sub_f32_e32 v34, v35, v213
	v_exp_f32_e32 v113, v50
	v_sub_f32_e32 v50, v67, v213
	v_exp_f32_e32 v107, v34
	v_sub_f32_e32 v34, v36, v213
	v_pk_add_f32 v[48:49], v[110:111], 0 op_sel_hi:[1,0]
	v_exp_f32_e32 v156, v50
	v_sub_f32_e32 v50, v66, v213
	v_exp_f32_e32 v118, v34
	v_sub_f32_e32 v34, v37, v213
	v_pk_add_f32 v[48:49], v[154:155], v[48:49]
	v_exp_f32_e32 v157, v50
	v_sub_f32_e32 v50, v65, v213
	v_exp_f32_e32 v119, v34
	v_sub_f32_e32 v34, v38, v213
	v_pk_add_f32 v[48:49], v[160:161], v[48:49]
	v_exp_f32_e32 v162, v50
	v_sub_f32_e32 v50, v64, v213
	v_sub_f32_e32 v32, v32, v213
	v_exp_f32_e32 v158, v34
	v_sub_f32_e32 v34, v39, v213
	v_pk_add_f32 v[48:49], v[164:165], v[48:49]
	v_exp_f32_e32 v163, v50
	v_exp_f32_e32 v78, v32
	v_sub_f32_e32 v32, v33, v213
	v_exp_f32_e32 v159, v34
	v_sub_f32_e32 v34, v40, v213
	v_pk_add_f32 v[48:49], v[102:103], v[48:49]
	v_exp_f32_e32 v79, v32
	v_exp_f32_e32 v68, v34
	v_sub_f32_e32 v34, v41, v213
	v_pk_add_f32 v[48:49], v[112:113], v[48:49]
	v_exp_f32_e32 v69, v34
	v_sub_f32_e32 v34, v42, v213
	v_sub_f32_e32 v18, v18, v213
	v_sub_f32_e32 v2, v2, v213
	v_pk_add_f32 v[48:49], v[156:157], v[48:49]
	v_exp_f32_e32 v76, v34
	v_sub_f32_e32 v34, v43, v213
	v_exp_f32_e32 v72, v18
	v_sub_f32_e32 v18, v19, v213
	v_exp_f32_e32 v60, v2
	v_sub_f32_e32 v2, v3, v213
	v_pk_add_f32 v[48:49], v[162:163], v[48:49]
	v_exp_f32_e32 v77, v34
	v_sub_f32_e32 v34, v44, v213
	v_exp_f32_e32 v73, v18
	v_sub_f32_e32 v18, v20, v213
	v_exp_f32_e32 v61, v2
	v_sub_f32_e32 v2, v4, v213
	v_pk_add_f32 v[32:33], v[78:79], v[48:49]
	v_exp_f32_e32 v104, v34
	v_sub_f32_e32 v34, v45, v213
	v_exp_f32_e32 v100, v18
	v_sub_f32_e32 v18, v21, v213
	v_exp_f32_e32 v66, v2
	v_sub_f32_e32 v2, v5, v213
	v_pk_add_f32 v[32:33], v[106:107], v[32:33]
	v_exp_f32_e32 v105, v34
	v_sub_f32_e32 v34, v46, v213
	v_exp_f32_e32 v101, v18
	v_sub_f32_e32 v18, v22, v213
	v_exp_f32_e32 v67, v2
	v_sub_f32_e32 v2, v6, v213
	v_pk_add_f32 v[32:33], v[118:119], v[32:33]
	v_exp_f32_e32 v114, v34
	v_sub_f32_e32 v34, v47, v213
	v_sub_f32_e32 v16, v16, v213
	v_exp_f32_e32 v108, v18
	v_sub_f32_e32 v18, v23, v213
	v_exp_f32_e32 v74, v2
	v_sub_f32_e32 v2, v7, v213
	v_pk_add_f32 v[32:33], v[158:159], v[32:33]
	v_exp_f32_e32 v115, v34
	v_exp_f32_e32 v64, v16
	v_sub_f32_e32 v16, v17, v213
	v_exp_f32_e32 v109, v18
	v_sub_f32_e32 v18, v24, v213
	v_exp_f32_e32 v75, v2
	v_sub_f32_e32 v2, v8, v213
	v_pk_add_f32 v[32:33], v[68:69], v[32:33]
	v_exp_f32_e32 v65, v16
	v_exp_f32_e32 v58, v18
	v_sub_f32_e32 v18, v25, v213
	v_exp_f32_e32 v48, v2
	v_sub_f32_e32 v2, v9, v213
	v_pk_add_f32 v[32:33], v[76:77], v[32:33]
	v_exp_f32_e32 v59, v18
	v_sub_f32_e32 v18, v26, v213
	v_exp_f32_e32 v49, v2
	v_sub_f32_e32 v2, v10, v213
	v_pk_add_f32 v[32:33], v[104:105], v[32:33]
	v_exp_f32_e32 v62, v18
	v_sub_f32_e32 v18, v27, v213
	v_exp_f32_e32 v50, v2
	v_sub_f32_e32 v2, v11, v213
	v_pk_add_f32 v[32:33], v[114:115], v[32:33]
	v_exp_f32_e32 v63, v18
	v_sub_f32_e32 v18, v28, v213
	v_exp_f32_e32 v51, v2
	v_sub_f32_e32 v2, v12, v213
	v_pk_add_f32 v[16:17], v[64:65], v[32:33]
	v_exp_f32_e32 v70, v18
	v_sub_f32_e32 v18, v29, v213
	v_exp_f32_e32 v52, v2
	v_sub_f32_e32 v2, v13, v213
	v_pk_add_f32 v[16:17], v[72:73], v[16:17]
	v_exp_f32_e32 v71, v18
	v_sub_f32_e32 v18, v30, v213
	v_exp_f32_e32 v53, v2
	v_sub_f32_e32 v2, v14, v213
	v_pk_add_f32 v[16:17], v[100:101], v[16:17]
	v_exp_f32_e32 v98, v18
	v_sub_f32_e32 v18, v31, v213
	v_sub_f32_e32 v0, v0, v213
	v_exp_f32_e32 v54, v2
	v_sub_f32_e32 v2, v15, v213
	v_pk_add_f32 v[16:17], v[108:109], v[16:17]
	v_exp_f32_e32 v99, v18
	v_exp_f32_e32 v56, v0
	v_sub_f32_e32 v0, v1, v213
	v_exp_f32_e32 v55, v2
	v_sub_f32_e32 v2, v167, v213
	v_pk_add_f32 v[16:17], v[58:59], v[16:17]
	v_exp_f32_e32 v57, v0
	v_exp_f32_e32 v40, v2
	v_sub_f32_e32 v2, v166, v213
	v_pk_add_f32 v[16:17], v[62:63], v[16:17]
	v_exp_f32_e32 v41, v2
	v_sub_f32_e32 v2, v168, v213
	v_pk_add_f32 v[16:17], v[70:71], v[16:17]
	v_exp_f32_e32 v42, v2
	v_sub_f32_e32 v2, v169, v213
	v_pk_add_f32 v[16:17], v[98:99], v[16:17]
	v_exp_f32_e32 v43, v2
	v_sub_f32_e32 v2, v170, v213
	v_pk_add_f32 v[0:1], v[56:57], v[16:17]
	v_exp_f32_e32 v44, v2
	v_sub_f32_e32 v2, v171, v213
	v_pk_add_f32 v[0:1], v[60:61], v[0:1]
	v_exp_f32_e32 v45, v2
	v_sub_f32_e32 v2, v172, v213
	v_pk_add_f32 v[0:1], v[66:67], v[0:1]
	v_exp_f32_e32 v46, v2
	v_sub_f32_e32 v2, v173, v213
	v_pk_add_f32 v[0:1], v[74:75], v[0:1]
	v_exp_f32_e32 v47, v2
	v_sub_f32_e32 v2, v174, v213
	v_pk_add_f32 v[0:1], v[48:49], v[0:1]
	v_exp_f32_e32 v32, v2
	v_sub_f32_e32 v2, v175, v213
	v_pk_add_f32 v[0:1], v[50:51], v[0:1]
	v_exp_f32_e32 v33, v2
	v_sub_f32_e32 v2, v176, v213
	v_pk_add_f32 v[0:1], v[52:53], v[0:1]
	v_exp_f32_e32 v34, v2
	v_sub_f32_e32 v2, v177, v213
	v_pk_add_f32 v[0:1], v[54:55], v[0:1]
	v_exp_f32_e32 v35, v2
	v_sub_f32_e32 v2, v178, v213
	v_pk_add_f32 v[0:1], v[40:41], v[0:1]
	v_exp_f32_e32 v36, v2
	v_sub_f32_e32 v2, v179, v213
	v_pk_add_f32 v[0:1], v[42:43], v[0:1]
	v_exp_f32_e32 v37, v2
	v_sub_f32_e32 v2, v180, v213
	v_pk_add_f32 v[0:1], v[44:45], v[0:1]
	v_exp_f32_e32 v38, v2
	v_sub_f32_e32 v2, v181, v213
	v_pk_add_f32 v[0:1], v[46:47], v[0:1]
	v_exp_f32_e32 v39, v2
	v_pk_add_f32 v[0:1], v[32:33], v[0:1]
	v_cvt_pk_bf16_f32 v16, v110, v111
	v_cvt_pk_bf16_f32 v17, v154, v155
	v_add_u32_e32 v154, 0x9000, v207
	v_pk_add_f32 v[0:1], v[34:35], v[0:1]
	v_cvt_pk_bf16_f32 v18, v160, v161
	v_cvt_pk_bf16_f32 v19, v164, v165
	v_add_u32_e32 v160, 0xd000, v207
	v_pk_add_f32 v[0:1], v[36:37], v[0:1]
	ds_read2_b64 v[20:23], v160 offset0:32 offset1:34
	v_pk_add_f32 v[0:1], v[38:39], v[0:1]
	s_nop 0
	v_add_f32_e32 v0, v0, v1
	ds_bpermute_b32 v1, v188, v0
	s_waitcnt lgkmcnt(0)
	v_add_f32_e32 v0, v0, v1
	v_sub_f32_e32 v1, v96, v213
	v_exp_f32_e32 v1, v1
	s_nop 0
	v_add_f32_e32 v96, v1, v0
	ds_read2_b64 v[0:3], v154 offset1:2
	v_cvt_pk_bf16_f32 v110, v102, v103
	v_cvt_pk_bf16_f32 v111, v112, v113
	v_cvt_pk_bf16_f32 v112, v156, v157
	v_cvt_pk_bf16_f32 v113, v162, v163
	ds_read2_b64 v[154:157], v154 offset0:4 offset1:6
	s_waitcnt lgkmcnt(1)
	v_mfma_f32_32x32x16_bf16 v[0:15], v[0:3], v[16:19], 0
	s_waitcnt lgkmcnt(0)
	v_mfma_f32_32x32x16_bf16 v[0:15], v[154:157], v[110:113], v[0:15]
	ds_read2_b64 v[154:157], v160 offset0:36 offset1:38
	v_mfma_f32_32x32x16_bf16 v[16:31], v[20:23], v[16:19], 0
	s_waitcnt lgkmcnt(0)
	v_mfma_f32_32x32x16_bf16 v[16:31], v[154:157], v[110:113], v[16:31]
	v_cvt_pk_bf16_f32 v110, v78, v79
	v_add_u32_e32 v78, 0x9000, v208
	v_cvt_pk_bf16_f32 v111, v106, v107
	v_cvt_pk_bf16_f32 v112, v118, v119
	v_cvt_pk_bf16_f32 v113, v158, v159
	ds_read2_b64 v[154:157], v78 offset1:2
	v_add_u32_e32 v106, 0xd000, v208
	s_waitcnt lgkmcnt(0)
	v_mfma_f32_32x32x16_bf16 v[0:15], v[154:157], v[110:113], v[0:15]
	ds_read2_b64 v[154:157], v106 offset0:32 offset1:34
	v_cvt_pk_bf16_f32 v102, v68, v69
	v_cvt_pk_bf16_f32 v103, v76, v77
	v_cvt_pk_bf16_f32 v104, v104, v105
	v_cvt_pk_bf16_f32 v105, v114, v115
	ds_read2_b64 v[76:79], v78 offset0:4 offset1:6
	s_waitcnt lgkmcnt(0)
	v_mfma_f32_32x32x16_bf16 v[0:15], v[76:79], v[102:105], v[0:15]
	ds_read2_b64 v[76:79], v106 offset0:36 offset1:38
	v_mfma_f32_32x32x16_bf16 v[16:31], v[154:157], v[110:113], v[16:31]
	s_waitcnt lgkmcnt(0)
	v_mfma_f32_32x32x16_bf16 v[16:31], v[76:79], v[102:105], v[16:31]
	v_cvt_pk_bf16_f32 v76, v64, v65
	v_add_u32_e32 v64, 0x9000, v209
	v_cvt_pk_bf16_f32 v77, v72, v73
	v_cvt_pk_bf16_f32 v78, v100, v101
	v_cvt_pk_bf16_f32 v79, v108, v109
	ds_read2_b64 v[100:103], v64 offset1:2
	v_add_u32_e32 v72, 0xd000, v209
	s_waitcnt lgkmcnt(0)
	v_mfma_f32_32x32x16_bf16 v[0:15], v[100:103], v[76:79], v[0:15]
	ds_read2_b64 v[100:103], v72 offset0:32 offset1:34
	v_cvt_pk_bf16_f32 v68, v58, v59
	v_cvt_pk_bf16_f32 v69, v62, v63
	v_cvt_pk_bf16_f32 v70, v70, v71
	v_cvt_pk_bf16_f32 v71, v98, v99
	ds_read2_b64 v[62:65], v64 offset0:4 offset1:6
	s_waitcnt lgkmcnt(0)
	v_mfma_f32_32x32x16_bf16 v[0:15], v[62:65], v[68:71], v[0:15]
	ds_read2_b64 v[62:65], v72 offset0:36 offset1:38
	v_cvt_pk_bf16_f32 v56, v56, v57
	v_cvt_pk_bf16_f32 v57, v60, v61
	v_cvt_pk_bf16_f32 v58, v66, v67
	v_cvt_pk_bf16_f32 v59, v74, v75
	v_mfma_f32_32x32x16_bf16 v[16:31], v[100:103], v[76:79], v[16:31]
	s_waitcnt lgkmcnt(0)
	v_mfma_f32_32x32x16_bf16 v[16:31], v[62:65], v[68:71], v[16:31]
	v_add_u32_e32 v64, 0x9000, v210
	ds_read2_b64 v[60:63], v64 offset1:2
	v_add_u32_e32 v65, 0xd000, v210
	s_waitcnt lgkmcnt(0)
	v_mfma_f32_32x32x16_bf16 v[0:15], v[60:63], v[56:59], v[0:15]
	ds_read2_b64 v[60:63], v65 offset0:32 offset1:34
	v_cvt_pk_bf16_f32 v48, v48, v49
	v_cvt_pk_bf16_f32 v49, v50, v51
	v_cvt_pk_bf16_f32 v50, v52, v53
	v_cvt_pk_bf16_f32 v51, v54, v55
	ds_read2_b64 v[52:55], v64 offset0:4 offset1:6
	s_waitcnt lgkmcnt(0)
	v_mfma_f32_32x32x16_bf16 v[0:15], v[52:55], v[48:51], v[0:15]
	ds_read2_b64 v[52:55], v65 offset0:36 offset1:38
	v_cvt_pk_bf16_f32 v40, v40, v41
	v_cvt_pk_bf16_f32 v41, v42, v43
	v_cvt_pk_bf16_f32 v42, v44, v45
	v_cvt_pk_bf16_f32 v43, v46, v47
	v_mfma_f32_32x32x16_bf16 v[16:31], v[60:63], v[56:59], v[16:31]
	s_waitcnt lgkmcnt(0)
	v_mfma_f32_32x32x16_bf16 v[16:31], v[52:55], v[48:51], v[16:31]
	v_add_u32_e32 v48, 0x9000, v211
	ds_read2_b64 v[44:47], v48 offset1:2
	v_add_u32_e32 v49, 0xd000, v211
	s_waitcnt lgkmcnt(0)
	v_mfma_f32_32x32x16_bf16 v[0:15], v[44:47], v[40:43], v[0:15]
	ds_read2_b64 v[44:47], v49 offset0:32 offset1:34
	v_cvt_pk_bf16_f32 v32, v32, v33
	v_cvt_pk_bf16_f32 v33, v34, v35
	v_cvt_pk_bf16_f32 v34, v36, v37
	v_cvt_pk_bf16_f32 v35, v38, v39
	ds_read2_b64 v[36:39], v48 offset0:4 offset1:6
	s_waitcnt lgkmcnt(0)
	v_mfma_f32_32x32x16_bf16 v[0:15], v[36:39], v[32:35], v[0:15]
	ds_read2_b64 v[36:39], v49 offset0:36 offset1:38
	v_mfma_f32_32x32x16_bf16 v[16:31], v[44:47], v[40:43], v[16:31]
	s_waitcnt lgkmcnt(0)
	v_mfma_f32_32x32x16_bf16 v[16:31], v[36:39], v[32:35], v[16:31]
	v_div_scale_f32 v32, s[68:69], v96, v96, 1.0
	v_rcp_f32_e32 v33, v32
	s_nop 0
	v_fma_f32 v34, -v32, v33, 1.0
	v_fmac_f32_e32 v33, v34, v33
	v_div_scale_f32 v34, vcc, 1.0, v96, 1.0
	v_mul_f32_e32 v35, v34, v33
	v_fma_f32 v36, -v32, v35, v34
	v_fmac_f32_e32 v35, v36, v33
	v_fma_f32 v32, -v32, v35, v34
	v_div_fmas_f32 v32, v32, v33, v35
	v_div_fixup_f32 v34, v32, v96, 1.0
	v_mul_f32_e32 v0, v0, v34
	v_mul_f32_e32 v1, v1, v34
	v_cvt_pk_bf16_f32 v0, v0, v1
	v_mul_f32_e32 v1, v2, v34
	v_mad_i64_i32 v[32:33], s[68:69], v153, s65, v[116:117]
	v_and_b32_e32 v36, 63, v251
	v_and_b32_e32 v35, 31, v251
	v_lshrrev_b32_e32 v37, 5, v36
	v_lshlrev_b32_e32 v37, 3, v37
	s_movk_i32 s58, 0x90
	v_mad_u32_u24 v35, v35, s58, v37
	s_movk_i32 s59, 0x1200
	v_mad_u32_u24 v35, v254, s59, v35
	v_add_u32_e32 v35, 0x12000, v35
	v_lshrrev_b32_e32 v37, 3, v36
	v_and_b32_e32 v40, 7, v36
	v_lshlrev_b32_e32 v40, 4, v40
	v_mad_u32_u24 v36, v37, s58, v40
	v_mad_u32_u24 v36, v254, s59, v36
	v_add_u32_e32 v36, 0x12000, v36
	s_movk_i32 s58, 0xc00
	v_mad_u32_u24 v37, v37, s58, v40
	v_readfirstlane_b32 s56, v32
	v_readfirstlane_b32 s57, v33
	v_mul_f32_e32 v2, v3, v34
	v_cvt_pk_bf16_f32 v1, v1, v2
	ds_write_b64 v35, v[0:1]
	v_mul_f32_e32 v0, v4, v34
	v_mul_f32_e32 v1, v5, v34
	v_cvt_pk_bf16_f32 v0, v0, v1
	v_mul_f32_e32 v1, v6, v34
	v_mul_f32_e32 v2, v7, v34
	v_cvt_pk_bf16_f32 v1, v1, v2
	ds_write_b64 v35, v[0:1] offset:16
	v_mul_f32_e32 v0, v8, v34
	v_mul_f32_e32 v1, v9, v34
	v_cvt_pk_bf16_f32 v0, v0, v1
	v_mul_f32_e32 v1, v10, v34
	v_mul_f32_e32 v2, v11, v34
	v_cvt_pk_bf16_f32 v1, v1, v2
	ds_write_b64 v35, v[0:1] offset:32
	v_mul_f32_e32 v0, v12, v34
	v_mul_f32_e32 v1, v13, v34
	v_cvt_pk_bf16_f32 v0, v0, v1
	v_mul_f32_e32 v1, v14, v34
	v_mul_f32_e32 v2, v15, v34
	v_cvt_pk_bf16_f32 v1, v1, v2
	ds_write_b64 v35, v[0:1] offset:48
	v_mul_f32_e32 v0, v16, v34
	v_mul_f32_e32 v1, v17, v34
	v_cvt_pk_bf16_f32 v0, v0, v1
	v_mul_f32_e32 v1, v18, v34
	v_mul_f32_e32 v2, v19, v34
	v_cvt_pk_bf16_f32 v1, v1, v2
	ds_write_b64 v35, v[0:1] offset:64
	v_mul_f32_e32 v0, v20, v34
	v_mul_f32_e32 v1, v21, v34
	v_cvt_pk_bf16_f32 v0, v0, v1
	v_mul_f32_e32 v1, v22, v34
	v_mul_f32_e32 v2, v23, v34
	v_cvt_pk_bf16_f32 v1, v1, v2
	ds_write_b64 v35, v[0:1] offset:80
	v_mul_f32_e32 v0, v24, v34
	v_mul_f32_e32 v1, v25, v34
	v_cvt_pk_bf16_f32 v0, v0, v1
	v_mul_f32_e32 v1, v26, v34
	v_mul_f32_e32 v2, v27, v34
	v_cvt_pk_bf16_f32 v1, v1, v2
	ds_write_b64 v35, v[0:1] offset:96
	v_mul_f32_e32 v0, v28, v34
	v_mul_f32_e32 v1, v29, v34
	v_cvt_pk_bf16_f32 v0, v0, v1
	v_mul_f32_e32 v1, v30, v34
	s_andn2_b64 vcc, exec, s[76:77]
	v_mul_f32_e32 v2, v31, v34
	v_cvt_pk_bf16_f32 v1, v1, v2
	ds_write_b64 v35, v[0:1] offset:112
	s_waitcnt lgkmcnt(0)
	ds_read_b128 v[0:3], v36
	ds_read_b128 v[4:7], v36 offset:1152
	ds_read_b128 v[8:11], v36 offset:2304
	ds_read_b128 v[12:15], v36 offset:3456
	s_waitcnt lgkmcnt(3)
	global_store_dwordx4 v37, v[0:3], s[56:57]
	s_add_u32 s56, s56, 0x6000
	s_addc_u32 s57, s57, 0
	s_waitcnt lgkmcnt(2)
	global_store_dwordx4 v37, v[4:7], s[56:57]
	s_add_u32 s56, s56, 0x6000
	s_addc_u32 s57, s57, 0
	s_waitcnt lgkmcnt(1)
	global_store_dwordx4 v37, v[8:11], s[56:57]
	s_add_u32 s56, s56, 0x6000
	s_addc_u32 s57, s57, 0
	s_waitcnt lgkmcnt(0)
	global_store_dwordx4 v37, v[12:15], s[56:57]
	s_nop 1
	s_barrier
	s_cbranch_vccz .LBB0_359

.LBB0_357:
	s_mov_b32 s64, 0xff800000
	v_cndmask_b32_e64 v72, v48, v212, s[2:3]
	v_cndmask_b32_e64 v216, v72, v48, s[4:5]
	v_max3_f32 v48, v158, s64, v157
	v_max3_f32 v48, v48, v156, v155
	v_max3_f32 v48, v48, v154, v119
	v_max3_f32 v48, v48, v118, v99
	v_max3_f32 v48, v48, v71, v70
	v_max3_f32 v48, v48, v69, v68
	v_max3_f32 v48, v48, v67, v66
	v_max3_f32 v48, v48, v65, v64
	v_max3_f32 v48, v48, v32, v33
	v_max3_f32 v48, v48, v34, v35
	v_max3_f32 v48, v48, v36, v37
	v_max3_f32 v48, v48, v38, v39
	v_max3_f32 v48, v48, v40, v41
	v_max3_f32 v48, v48, v42, v43
	v_max3_f32 v48, v48, v44, v45
	v_max3_f32 v48, v48, v46, v47
	v_max3_f32 v48, v48, v16, v17
	v_max3_f32 v48, v48, v18, v19
	v_max3_f32 v48, v48, v20, v21
	v_max3_f32 v48, v48, v22, v23
	v_max3_f32 v48, v48, v24, v25
	v_max3_f32 v48, v48, v26, v27
	v_max3_f32 v48, v48, v28, v29
	v_max3_f32 v48, v48, v30, v31
	v_max3_f32 v48, v48, v0, v1
	v_max3_f32 v48, v48, v2, v3
	v_max3_f32 v48, v48, v4, v5
	v_max3_f32 v48, v48, v6, v7
	v_max3_f32 v48, v48, v8, v9
	v_max3_f32 v48, v48, v10, v11
	v_max3_f32 v48, v48, v12, v13
	v_cndmask_b32_e64 v215, v212, v49, s[4:5]
	v_max3_f32 v48, v48, v14, v15
	v_cndmask_b32_e64 v217, v50, v212, s[6:7]
	v_cndmask_b32_e64 v218, v51, v212, s[8:9]
	v_max3_f32 v48, v48, v216, v215
	v_cndmask_b32_e64 v219, v52, v212, s[10:11]
	v_cndmask_b32_e64 v220, v53, v212, s[12:13]
	v_max3_f32 v48, v48, v217, v218
	v_cndmask_b32_e64 v221, v54, v212, s[14:15]
	v_cndmask_b32_e64 v222, v55, v212, s[16:17]
	v_max3_f32 v48, v48, v219, v220
	v_cndmask_b32_e64 v223, v56, v212, s[18:19]
	v_cndmask_b32_e64 v224, v57, v212, s[20:21]
	v_max3_f32 v48, v48, v221, v222
	v_cndmask_b32_e64 v225, v58, v212, s[22:23]
	v_cndmask_b32_e64 v226, v59, v212, s[24:25]
	v_max3_f32 v48, v48, v223, v224
	v_cndmask_b32_e64 v227, v60, v212, s[26:27]
	v_cndmask_b32_e64 v228, v61, v212, s[28:29]
	v_max3_f32 v48, v48, v225, v226
	v_cndmask_b32_e64 v229, v62, v212, s[30:31]
	v_cndmask_b32_e64 v230, v63, v212, s[34:35]
	v_max3_f32 v48, v48, v227, v228
	v_max3_f32 v48, v48, v229, v230
	ds_bpermute_b32 v49, v188, v48
	v_mul_f32_e32 v96, 0x3fb8aa3b, v214
	v_or_b32_e32 v213, s89, v98
	s_mov_b32 s55, 0x3fb8aa3b
	s_lshl_b32 s94, s69, 1
	s_waitcnt lgkmcnt(0)
	v_max3_f32 v231, v48, v49, v96
	v_sub_f32_e32 v50, v156, v231
	v_exp_f32_e32 v170, v50
	v_sub_f32_e32 v50, v155, v231
	v_exp_f32_e32 v171, v50
	v_sub_f32_e32 v50, v154, v231
	v_exp_f32_e32 v176, v50
	v_sub_f32_e32 v50, v119, v231
	v_exp_f32_e32 v177, v50
	v_sub_f32_e32 v50, v118, v231
	v_sub_f32_e32 v48, v158, v231
	v_exp_f32_e32 v180, v50
	v_sub_f32_e32 v50, v99, v231
	v_exp_f32_e32 v162, v48
	v_sub_f32_e32 v48, v157, v231
	v_exp_f32_e32 v181, v50
	v_sub_f32_e32 v50, v71, v231
	v_exp_f32_e32 v163, v48
	v_exp_f32_e32 v154, v50
	v_sub_f32_e32 v50, v70, v231
	v_exp_f32_e32 v155, v50
	v_sub_f32_e32 v50, v69, v231
	v_sub_f32_e32 v34, v34, v231
	v_exp_f32_e32 v164, v50
	v_sub_f32_e32 v50, v68, v231
	v_exp_f32_e32 v158, v34
	v_sub_f32_e32 v34, v35, v231
	v_exp_f32_e32 v165, v50
	v_sub_f32_e32 v50, v67, v231
	v_exp_f32_e32 v159, v34
	v_sub_f32_e32 v34, v36, v231
	v_pk_add_f32 v[48:49], v[162:163], 0 op_sel_hi:[1,0]
	v_exp_f32_e32 v172, v50
	v_sub_f32_e32 v50, v66, v231
	v_exp_f32_e32 v166, v34
	v_sub_f32_e32 v34, v37, v231
	v_pk_add_f32 v[48:49], v[170:171], v[48:49]
	v_exp_f32_e32 v173, v50
	v_sub_f32_e32 v50, v65, v231
	v_exp_f32_e32 v167, v34
	v_sub_f32_e32 v34, v38, v231
	v_pk_add_f32 v[48:49], v[176:177], v[48:49]
	v_exp_f32_e32 v178, v50
	v_sub_f32_e32 v50, v64, v231
	v_sub_f32_e32 v32, v32, v231
	v_exp_f32_e32 v174, v34
	v_sub_f32_e32 v34, v39, v231
	v_pk_add_f32 v[48:49], v[180:181], v[48:49]
	v_exp_f32_e32 v179, v50
	v_exp_f32_e32 v78, v32
	v_sub_f32_e32 v32, v33, v231
	v_exp_f32_e32 v175, v34
	v_sub_f32_e32 v34, v40, v231
	v_pk_add_f32 v[48:49], v[154:155], v[48:49]
	v_exp_f32_e32 v79, v32
	v_exp_f32_e32 v70, v34
	v_sub_f32_e32 v34, v41, v231
	v_pk_add_f32 v[48:49], v[164:165], v[48:49]
	v_exp_f32_e32 v71, v34
	v_sub_f32_e32 v34, v42, v231
	v_sub_f32_e32 v18, v18, v231
	v_sub_f32_e32 v2, v2, v231
	v_pk_add_f32 v[48:49], v[172:173], v[48:49]
	v_exp_f32_e32 v76, v34
	v_sub_f32_e32 v34, v43, v231
	v_exp_f32_e32 v74, v18
	v_sub_f32_e32 v18, v19, v231
	v_exp_f32_e32 v60, v2
	v_sub_f32_e32 v2, v3, v231
	v_pk_add_f32 v[48:49], v[178:179], v[48:49]
	v_exp_f32_e32 v77, v34
	v_sub_f32_e32 v34, v44, v231
	v_exp_f32_e32 v75, v18
	v_sub_f32_e32 v18, v20, v231
	v_exp_f32_e32 v61, v2
	v_sub_f32_e32 v2, v4, v231
	v_pk_add_f32 v[32:33], v[78:79], v[48:49]
	v_exp_f32_e32 v156, v34
	v_sub_f32_e32 v34, v45, v231
	v_exp_f32_e32 v98, v18
	v_sub_f32_e32 v18, v21, v231
	v_exp_f32_e32 v66, v2
	v_sub_f32_e32 v2, v5, v231
	v_pk_add_f32 v[32:33], v[158:159], v[32:33]
	v_exp_f32_e32 v157, v34
	v_sub_f32_e32 v34, v46, v231
	v_exp_f32_e32 v99, v18
	v_sub_f32_e32 v18, v22, v231
	v_exp_f32_e32 v67, v2
	v_sub_f32_e32 v2, v6, v231
	v_pk_add_f32 v[32:33], v[166:167], v[32:33]
	v_exp_f32_e32 v168, v34
	v_sub_f32_e32 v34, v47, v231
	v_sub_f32_e32 v16, v16, v231
	v_exp_f32_e32 v160, v18
	v_sub_f32_e32 v18, v23, v231
	v_exp_f32_e32 v68, v2
	v_sub_f32_e32 v2, v7, v231
	v_pk_add_f32 v[32:33], v[174:175], v[32:33]
	v_exp_f32_e32 v169, v34
	v_exp_f32_e32 v64, v16
	v_sub_f32_e32 v16, v17, v231
	v_exp_f32_e32 v161, v18
	v_sub_f32_e32 v18, v24, v231
	v_exp_f32_e32 v69, v2
	v_sub_f32_e32 v2, v8, v231
	v_pk_add_f32 v[32:33], v[70:71], v[32:33]
	v_exp_f32_e32 v65, v16
	v_exp_f32_e32 v58, v18
	v_sub_f32_e32 v18, v25, v231
	v_exp_f32_e32 v48, v2
	v_sub_f32_e32 v2, v9, v231
	v_pk_add_f32 v[32:33], v[76:77], v[32:33]
	v_exp_f32_e32 v59, v18
	v_sub_f32_e32 v18, v26, v231
	v_exp_f32_e32 v49, v2
	v_sub_f32_e32 v2, v10, v231
	v_pk_add_f32 v[32:33], v[156:157], v[32:33]
	v_exp_f32_e32 v62, v18
	v_sub_f32_e32 v18, v27, v231
	v_exp_f32_e32 v50, v2
	v_sub_f32_e32 v2, v11, v231
	v_pk_add_f32 v[32:33], v[168:169], v[32:33]
	v_exp_f32_e32 v63, v18
	v_sub_f32_e32 v18, v28, v231
	v_exp_f32_e32 v51, v2
	v_sub_f32_e32 v2, v12, v231
	v_pk_add_f32 v[16:17], v[64:65], v[32:33]
	v_exp_f32_e32 v72, v18
	v_sub_f32_e32 v18, v29, v231
	v_exp_f32_e32 v52, v2
	v_sub_f32_e32 v2, v13, v231
	v_pk_add_f32 v[16:17], v[74:75], v[16:17]
	v_exp_f32_e32 v73, v18
	v_sub_f32_e32 v18, v30, v231
	v_exp_f32_e32 v53, v2
	v_sub_f32_e32 v2, v14, v231
	v_pk_add_f32 v[16:17], v[98:99], v[16:17]
	v_exp_f32_e32 v118, v18
	v_sub_f32_e32 v18, v31, v231
	v_sub_f32_e32 v0, v0, v231
	v_exp_f32_e32 v54, v2
	v_sub_f32_e32 v2, v15, v231
	v_pk_add_f32 v[16:17], v[160:161], v[16:17]
	v_exp_f32_e32 v119, v18
	v_exp_f32_e32 v56, v0
	v_sub_f32_e32 v0, v1, v231
	v_exp_f32_e32 v55, v2
	v_sub_f32_e32 v2, v216, v231
	v_pk_add_f32 v[16:17], v[58:59], v[16:17]
	v_exp_f32_e32 v57, v0
	v_exp_f32_e32 v40, v2
	v_sub_f32_e32 v2, v215, v231
	v_pk_add_f32 v[16:17], v[62:63], v[16:17]
	v_exp_f32_e32 v41, v2
	v_sub_f32_e32 v2, v217, v231
	v_pk_add_f32 v[16:17], v[72:73], v[16:17]
	v_exp_f32_e32 v42, v2
	v_sub_f32_e32 v2, v218, v231
	v_pk_add_f32 v[16:17], v[118:119], v[16:17]
	v_exp_f32_e32 v43, v2
	v_sub_f32_e32 v2, v219, v231
	v_pk_add_f32 v[0:1], v[56:57], v[16:17]
	v_exp_f32_e32 v44, v2
	v_sub_f32_e32 v2, v220, v231
	v_pk_add_f32 v[0:1], v[60:61], v[0:1]
	v_exp_f32_e32 v45, v2
	v_sub_f32_e32 v2, v221, v231
	v_pk_add_f32 v[0:1], v[66:67], v[0:1]
	v_exp_f32_e32 v46, v2
	v_sub_f32_e32 v2, v222, v231
	v_pk_add_f32 v[0:1], v[68:69], v[0:1]
	v_exp_f32_e32 v47, v2
	v_sub_f32_e32 v2, v223, v231
	v_pk_add_f32 v[0:1], v[48:49], v[0:1]
	v_exp_f32_e32 v32, v2
	v_sub_f32_e32 v2, v224, v231
	v_pk_add_f32 v[0:1], v[50:51], v[0:1]
	v_exp_f32_e32 v33, v2
	v_sub_f32_e32 v2, v225, v231
	v_pk_add_f32 v[0:1], v[52:53], v[0:1]
	v_exp_f32_e32 v34, v2
	v_sub_f32_e32 v2, v226, v231
	v_pk_add_f32 v[0:1], v[54:55], v[0:1]
	v_exp_f32_e32 v35, v2
	v_sub_f32_e32 v2, v227, v231
	v_pk_add_f32 v[0:1], v[40:41], v[0:1]
	v_exp_f32_e32 v36, v2
	v_sub_f32_e32 v2, v228, v231
	v_pk_add_f32 v[0:1], v[42:43], v[0:1]
	v_exp_f32_e32 v37, v2
	v_sub_f32_e32 v2, v229, v231
	v_pk_add_f32 v[0:1], v[44:45], v[0:1]
	v_exp_f32_e32 v38, v2
	v_sub_f32_e32 v2, v230, v231
	v_pk_add_f32 v[0:1], v[46:47], v[0:1]
	v_exp_f32_e32 v39, v2
	v_pk_add_f32 v[0:1], v[32:33], v[0:1]
	v_cvt_pk_bf16_f32 v16, v162, v163
	v_cvt_pk_bf16_f32 v17, v170, v171
	v_add_u32_e32 v170, 0x9000, v197
	v_pk_add_f32 v[0:1], v[34:35], v[0:1]
	v_cvt_pk_bf16_f32 v18, v176, v177
	v_cvt_pk_bf16_f32 v19, v180, v181
	v_add_u32_e32 v176, 0xd000, v197
	v_pk_add_f32 v[0:1], v[36:37], v[0:1]
	ds_read2_b64 v[20:23], v176 offset0:32 offset1:34
	v_pk_add_f32 v[0:1], v[38:39], v[0:1]
	v_lshl_add_u64 v[116:117], v[146:147], 0, s[94:95]
	v_add_f32_e32 v0, v0, v1
	ds_bpermute_b32 v1, v188, v0
	s_mov_b32 s97, s0
	v_readlane_b32 s0, v255, 15
	s_waitcnt lgkmcnt(0)
	v_add_f32_e32 v0, v0, v1
	v_fma_f32 v1, v214, s55, -v231
	v_exp_f32_e32 v1, v1
	s_nop 0
	v_add_f32_e32 v214, v1, v0
	ds_read2_b64 v[0:3], v170 offset1:2
	v_cvt_pk_bf16_f32 v162, v154, v155
	v_cvt_pk_bf16_f32 v163, v164, v165
	v_cvt_pk_bf16_f32 v164, v172, v173
	v_cvt_pk_bf16_f32 v165, v178, v179
	ds_read2_b64 v[170:173], v170 offset0:4 offset1:6
	s_waitcnt lgkmcnt(1)
	v_mfma_f32_32x32x16_bf16 v[0:15], v[0:3], v[16:19], 0
	s_waitcnt lgkmcnt(0)
	v_mfma_f32_32x32x16_bf16 v[0:15], v[170:173], v[162:165], v[0:15]
	ds_read2_b64 v[170:173], v176 offset0:36 offset1:38
	v_mfma_f32_32x32x16_bf16 v[16:31], v[20:23], v[16:19], 0
	s_waitcnt lgkmcnt(0)
	v_mfma_f32_32x32x16_bf16 v[16:31], v[170:173], v[162:165], v[16:31]
	v_cvt_pk_bf16_f32 v162, v78, v79
	v_add_u32_e32 v78, 0x9000, v198
	v_cvt_pk_bf16_f32 v163, v158, v159
	v_cvt_pk_bf16_f32 v164, v166, v167
	v_cvt_pk_bf16_f32 v165, v174, v175
	ds_read2_b64 v[170:173], v78 offset1:2
	v_add_u32_e32 v158, 0xd000, v198
	s_waitcnt lgkmcnt(0)
	v_mfma_f32_32x32x16_bf16 v[0:15], v[170:173], v[162:165], v[0:15]
	ds_read2_b64 v[170:173], v158 offset0:32 offset1:34
	v_cvt_pk_bf16_f32 v154, v70, v71
	v_cvt_pk_bf16_f32 v155, v76, v77
	v_cvt_pk_bf16_f32 v156, v156, v157
	v_cvt_pk_bf16_f32 v157, v168, v169
	ds_read2_b64 v[76:79], v78 offset0:4 offset1:6
	s_waitcnt lgkmcnt(0)
	v_mfma_f32_32x32x16_bf16 v[0:15], v[76:79], v[154:157], v[0:15]
	ds_read2_b64 v[76:79], v158 offset0:36 offset1:38
	v_mfma_f32_32x32x16_bf16 v[16:31], v[170:173], v[162:165], v[16:31]
	s_waitcnt lgkmcnt(0)
	v_mfma_f32_32x32x16_bf16 v[16:31], v[76:79], v[154:157], v[16:31]
	v_cvt_pk_bf16_f32 v76, v64, v65
	v_add_u32_e32 v64, 0x9000, v199
	v_cvt_pk_bf16_f32 v77, v74, v75
	v_cvt_pk_bf16_f32 v78, v98, v99
	v_cvt_pk_bf16_f32 v79, v160, v161
	ds_read2_b64 v[154:157], v64 offset1:2
	v_add_u32_e32 v74, 0xd000, v199
	s_waitcnt lgkmcnt(0)
	v_mfma_f32_32x32x16_bf16 v[0:15], v[154:157], v[76:79], v[0:15]
	ds_read2_b64 v[154:157], v74 offset0:32 offset1:34
	v_cvt_pk_bf16_f32 v70, v58, v59
	v_cvt_pk_bf16_f32 v71, v62, v63
	v_cvt_pk_bf16_f32 v72, v72, v73
	v_cvt_pk_bf16_f32 v73, v118, v119
	ds_read2_b64 v[62:65], v64 offset0:4 offset1:6
	v_or_b32_e32 v118, s0, v153
	s_waitcnt lgkmcnt(0)
	v_mfma_f32_32x32x16_bf16 v[0:15], v[62:65], v[70:73], v[0:15]
	ds_read2_b64 v[62:65], v74 offset0:36 offset1:38
	v_cvt_pk_bf16_f32 v56, v56, v57
	v_cvt_pk_bf16_f32 v57, v60, v61
	v_cvt_pk_bf16_f32 v58, v66, v67
	v_cvt_pk_bf16_f32 v59, v68, v69
	v_and_b32_e32 v67, 0xffff0000, v103
	v_and_b32_e32 v66, 0xffff0000, v107
	v_mfma_f32_32x32x16_bf16 v[16:31], v[154:157], v[76:79], v[16:31]
	v_lshlrev_b32_e32 v155, 16, v100
	v_lshlrev_b32_e32 v154, 16, v104
	v_and_b32_e32 v79, 0xffff0000, v102
	v_mul_f32_e64 v156, v154, v154
	v_mul_f32_e64 v157, v155, v155
	v_and_b32_e32 v78, 0xffff0000, v106
	v_pk_mul_f32 v[98:99], v[78:79], v[78:79]
	v_pk_mul_f32 v[68:69], v[66:67], v[66:67]
	s_waitcnt lgkmcnt(0)
	v_mfma_f32_32x32x16_bf16 v[16:31], v[62:65], v[70:73], v[16:31]
	v_add_u32_e32 v64, 0x9000, v200
	ds_read2_b64 v[60:63], v64 offset1:2
	v_add_u32_e32 v65, 0xd000, v200
	v_lshlrev_b32_e32 v71, 16, v102
	v_lshlrev_b32_e32 v102, 16, v105
	v_lshlrev_b32_e32 v70, 16, v106
	v_pk_mul_f32 v[72:73], v[70:71], v[70:71]
	s_waitcnt lgkmcnt(0)
	v_mfma_f32_32x32x16_bf16 v[0:15], v[60:63], v[56:59], v[0:15]
	ds_read2_b64 v[60:63], v65 offset0:32 offset1:34
	v_cvt_pk_bf16_f32 v48, v48, v49
	v_cvt_pk_bf16_f32 v49, v50, v51
	v_cvt_pk_bf16_f32 v50, v52, v53
	v_cvt_pk_bf16_f32 v51, v54, v55
	ds_read2_b64 v[52:55], v64 offset0:4 offset1:6
	s_waitcnt lgkmcnt(0)
	v_mfma_f32_32x32x16_bf16 v[0:15], v[52:55], v[48:51], v[0:15]
	ds_read2_b64 v[52:55], v65 offset0:36 offset1:38
	v_cvt_pk_bf16_f32 v40, v40, v41
	v_cvt_pk_bf16_f32 v41, v42, v43
	v_cvt_pk_bf16_f32 v42, v44, v45
	v_cvt_pk_bf16_f32 v43, v46, v47
	v_mfma_f32_32x32x16_bf16 v[16:31], v[60:63], v[56:59], v[16:31]
	v_lshlrev_b32_e32 v59, 16, v103
	v_lshlrev_b32_e32 v103, 16, v101
	v_lshlrev_b32_e32 v58, 16, v107
	v_mul_f32_e64 v106, v102, v102
	v_mul_f32_e64 v107, v103, v103
	v_pk_mul_f32 v[60:61], v[58:59], v[58:59]
	s_waitcnt lgkmcnt(0)
	v_mfma_f32_32x32x16_bf16 v[16:31], v[52:55], v[48:51], v[16:31]
	v_add_u32_e32 v48, 0x9000, v201
	ds_read2_b64 v[44:47], v48 offset1:2
	v_add_u32_e32 v49, 0xd000, v201
	s_waitcnt lgkmcnt(0)
	v_mfma_f32_32x32x16_bf16 v[0:15], v[44:47], v[40:43], v[0:15]
	ds_read2_b64 v[44:47], v49 offset0:32 offset1:34
	v_cvt_pk_bf16_f32 v32, v32, v33
	v_cvt_pk_bf16_f32 v33, v34, v35
	v_cvt_pk_bf16_f32 v34, v36, v37
	v_cvt_pk_bf16_f32 v35, v38, v39
	ds_read2_b64 v[36:39], v48 offset0:4 offset1:6
	s_waitcnt lgkmcnt(0)
	v_mfma_f32_32x32x16_bf16 v[0:15], v[36:39], v[32:35], v[0:15]
	ds_read2_b64 v[36:39], v49 offset0:36 offset1:38
	v_mfma_f32_32x32x16_bf16 v[16:31], v[44:47], v[40:43], v[16:31]
	v_lshlrev_b32_e32 v42, 16, v112
	v_lshlrev_b32_e32 v43, 16, v108
	v_mul_f32_e64 v54, v42, v42
	v_mul_f32_e64 v55, v43, v43
	s_waitcnt lgkmcnt(0)
	v_mfma_f32_32x32x16_bf16 v[16:31], v[36:39], v[32:35], v[16:31]
	v_div_scale_f32 v32, s[68:69], v214, v214, 1.0
	v_rcp_f32_e32 v33, v32
	v_lshlrev_b32_e32 v38, 16, v113
	v_mov_b32_e32 v41, v38
	v_lshlrev_b32_e32 v39, 16, v109
	v_fma_f32 v34, -v32, v33, 1.0
	v_fmac_f32_e32 v33, v34, v33
	v_div_scale_f32 v34, vcc, 1.0, v214, 1.0
	v_mul_f32_e32 v35, v34, v33
	v_fma_f32 v36, -v32, v35, v34
	v_fmac_f32_e32 v35, v36, v33
	v_fma_f32 v32, -v32, v35, v34
	v_div_fmas_f32 v32, v32, v33, v35
	v_div_fixup_f32 v34, v32, v214, 1.0
	v_mul_f32_e32 v0, v0, v34
	v_mul_f32_e32 v1, v1, v34
	v_cvt_pk_bf16_f32 v0, v0, v1
	v_mul_f32_e32 v1, v2, v34
	v_mad_i64_i32 v[32:33], s[68:69], v213, s65, v[116:117]
	v_and_b32_e32 v36, 63, v251
	v_and_b32_e32 v35, 31, v251
	v_lshrrev_b32_e32 v37, 5, v36
	v_lshlrev_b32_e32 v37, 3, v37
	s_movk_i32 s58, 0x90
	v_mad_u32_u24 v35, v35, s58, v37
	s_movk_i32 s59, 0x1200
	v_mad_u32_u24 v35, v254, s59, v35
	v_add_u32_e32 v35, 0x12000, v35
	v_lshrrev_b32_e32 v37, 3, v36
	v_and_b32_e32 v40, 7, v36
	v_lshlrev_b32_e32 v40, 4, v40
	v_mad_u32_u24 v36, v37, s58, v40
	v_mad_u32_u24 v36, v254, s59, v36
	v_add_u32_e32 v36, 0x12000, v36
	s_movk_i32 s58, 0xc00
	v_mad_u32_u24 v37, v37, s58, v40
	v_readfirstlane_b32 s56, v32
	v_readfirstlane_b32 s57, v33
	v_mul_f32_e32 v2, v3, v34
	v_cvt_pk_bf16_f32 v1, v1, v2
	ds_write_b64 v35, v[0:1]
	v_mul_f32_e32 v0, v4, v34
	v_mul_f32_e32 v1, v5, v34
	v_cvt_pk_bf16_f32 v0, v0, v1
	v_mul_f32_e32 v1, v6, v34
	v_mul_f32_e32 v2, v7, v34
	v_cvt_pk_bf16_f32 v1, v1, v2
	ds_write_b64 v35, v[0:1] offset:16
	v_mul_f32_e32 v0, v8, v34
	v_mul_f32_e32 v1, v9, v34
	v_cvt_pk_bf16_f32 v0, v0, v1
	v_mul_f32_e32 v1, v10, v34
	v_mul_f32_e32 v2, v11, v34
	v_cvt_pk_bf16_f32 v1, v1, v2
	ds_write_b64 v35, v[0:1] offset:32
	v_mul_f32_e32 v0, v12, v34
	v_mul_f32_e32 v1, v13, v34
	v_cvt_pk_bf16_f32 v0, v0, v1
	v_mul_f32_e32 v1, v14, v34
	v_mul_f32_e32 v2, v15, v34
	v_cvt_pk_bf16_f32 v1, v1, v2
	ds_write_b64 v35, v[0:1] offset:48
	v_mul_f32_e32 v0, v16, v34
	v_mul_f32_e32 v1, v17, v34
	v_cvt_pk_bf16_f32 v0, v0, v1
	v_mul_f32_e32 v1, v18, v34
	v_mul_f32_e32 v2, v19, v34
	v_cvt_pk_bf16_f32 v1, v1, v2
	ds_write_b64 v35, v[0:1] offset:64
	v_mul_f32_e32 v0, v20, v34
	v_mul_f32_e32 v1, v21, v34
	v_cvt_pk_bf16_f32 v0, v0, v1
	v_mul_f32_e32 v1, v22, v34
	v_mul_f32_e32 v2, v23, v34
	v_cvt_pk_bf16_f32 v1, v1, v2
	ds_write_b64 v35, v[0:1] offset:80
	v_mul_f32_e32 v0, v24, v34
	v_mul_f32_e32 v1, v25, v34
	v_cvt_pk_bf16_f32 v0, v0, v1
	v_mul_f32_e32 v1, v26, v34
	v_mul_f32_e32 v2, v27, v34
	v_cvt_pk_bf16_f32 v1, v1, v2
	ds_write_b64 v35, v[0:1] offset:96
	v_mul_f32_e32 v0, v28, v34
	v_mul_f32_e32 v1, v29, v34
	v_cvt_pk_bf16_f32 v0, v0, v1
	v_mul_f32_e32 v1, v30, v34
	v_mul_f32_e32 v2, v31, v34
	v_cvt_pk_bf16_f32 v1, v1, v2
	ds_write_b64 v35, v[0:1] offset:112
	s_waitcnt lgkmcnt(0)
	ds_read_b128 v[0:3], v36
	ds_read_b128 v[4:7], v36 offset:1152
	ds_read_b128 v[8:11], v36 offset:2304
	ds_read_b128 v[12:15], v36 offset:3456
	s_waitcnt lgkmcnt(3)
	global_store_dwordx4 v37, v[0:3], s[56:57]
	s_add_u32 s56, s56, 0x6000
	s_addc_u32 s57, s57, 0
	s_waitcnt lgkmcnt(2)
	global_store_dwordx4 v37, v[4:7], s[56:57]
	s_add_u32 s56, s56, 0x6000
	s_addc_u32 s57, s57, 0
	s_waitcnt lgkmcnt(1)
	global_store_dwordx4 v37, v[8:11], s[56:57]
	s_add_u32 s56, s56, 0x6000
	s_addc_u32 s57, s57, 0
	s_waitcnt lgkmcnt(0)
	global_store_dwordx4 v37, v[12:15], s[56:57]
	s_nop 1
	global_load_dwordx4 v[0:3], v[150:151], off offset:16
	s_nop 0
	global_load_dwordx4 v[16:19], v[150:151], off
	global_load_dwordx4 v[4:7], v[150:151], off offset:144
	global_load_dwordx4 v[20:23], v[150:151], off offset:128
	v_lshlrev_b32_e32 v28, 5, v118
	v_or_b32_e32 v8, v28, v126
	v_lshlrev_b32_e32 v29, 2, v8
	global_load_dwordx4 v[8:11], v29, s[82:83] offset:16
	global_load_dwordx4 v[24:27], v29, s[82:83]
	global_load_dwordx4 v[12:15], v29, s[92:93] offset:16
	global_load_dwordx4 v[44:47], v29, s[92:93]
	v_or_b32_e32 v28, v28, v127
	v_lshlrev_b32_e32 v119, 2, v28
	v_lshlrev_b32_e32 v30, 16, v115
	v_and_b32_e32 v28, 0xffff0000, v115
	v_mov_b32_e32 v32, v28
	v_mov_b32_e32 v33, v30
	v_pk_mul_f32 v[48:49], v[32:33], v[32:33]
	v_lshlrev_b32_e32 v34, 16, v114
	v_and_b32_e32 v32, 0xffff0000, v114
	v_mov_b32_e32 v36, v32
	v_mov_b32_e32 v37, v34
	v_pk_mul_f32 v[50:51], v[36:37], v[36:37]
	v_and_b32_e32 v36, 0xffff0000, v113
	v_mov_b32_e32 v40, v36
	v_and_b32_e32 v113, 0xffff0000, v101
	v_and_b32_e32 v101, 0xffff0000, v100
	v_and_b32_e32 v100, 0xffff0000, v104
	v_pk_mul_f32 v[52:53], v[40:41], v[40:41]
	v_and_b32_e32 v40, 0xffff0000, v112
	v_and_b32_e32 v112, 0xffff0000, v105
	v_pk_mul_f32 v[104:105], v[100:101], v[100:101]
	v_pk_mul_f32 v[114:115], v[112:113], v[112:113]
	v_and_b32_e32 v41, 0xffff0000, v108
	v_pk_mul_f32 v[56:57], v[40:41], v[40:41]
	v_and_b32_e32 v37, 0xffff0000, v109
	v_lshlrev_b32_e32 v35, 16, v110
	v_and_b32_e32 v33, 0xffff0000, v110
	v_lshlrev_b32_e32 v31, 16, v111
	v_and_b32_e32 v29, 0xffff0000, v111
	s_andn2_b64 vcc, exec, s[78:79]
	s_waitcnt vmcnt(7)
	v_mov_b32_e32 v75, v0
	v_add_f32_e32 v0, v157, v105
	v_add_f32_e32 v0, v107, v0
	v_add_f32_e32 v0, v115, v0
	v_add_f32_e32 v0, v73, v0
	v_add_f32_e32 v0, v99, v0
	v_add_f32_e32 v0, v61, v0
	v_add_f32_e32 v0, v69, v0
	v_add_f32_e32 v0, v55, v0
	v_add_f32_e32 v0, v57, v0
	v_fmac_f32_e32 v0, v39, v39
	v_fmac_f32_e32 v0, v37, v37
	v_fmac_f32_e32 v0, v35, v35
	v_fmac_f32_e32 v0, v33, v33
	v_fmac_f32_e32 v0, v31, v31
	v_fmac_f32_e32 v0, v29, v29
	v_add_f32_e32 v0, v156, v0
	v_add_f32_e32 v0, v104, v0
	v_add_f32_e32 v0, v106, v0
	v_add_f32_e32 v0, v114, v0
	v_add_f32_e32 v0, v72, v0
	v_add_f32_e32 v0, v98, v0
	v_add_f32_e32 v0, v60, v0
	v_add_f32_e32 v0, v68, v0
	v_add_f32_e32 v0, v54, v0
	v_add_f32_e32 v0, v56, v0
	v_add_f32_e32 v0, v53, v0
	v_add_f32_e32 v0, v52, v0
	v_add_f32_e32 v0, v51, v0
	v_add_f32_e32 v0, v50, v0
	v_add_f32_e32 v0, v49, v0
	v_add_f32_e32 v0, v48, v0
	v_mov_b32_e32 v63, v2
	ds_bpermute_b32 v2, v188, v0
	s_waitcnt vmcnt(5)
	v_mov_b32_e32 v74, v4
	s_waitcnt vmcnt(4)
	v_mov_b32_e32 v158, v20
	v_mov_b32_e32 v159, v16
	s_waitcnt vmcnt(2)
	v_mov_b32_e32 v160, v24
	s_waitcnt lgkmcnt(0)
	v_add_f32_e32 v0, v0, v2
	v_fmamk_f32 v0, v0, 0x3c800000, v189
	v_rsq_f32_e32 v0, v0
	s_waitcnt vmcnt(0)
	v_mov_b32_e32 v161, v44
	v_mov_b32_e32 v50, v44
	v_mov_b32_e32 v51, v24
	v_mul_f32_e32 v4, 0x3e38aa3b, v0
	v_pk_mul_f32 v[48:49], v[4:5], v[154:155] op_sel_hi:[0,1]
	v_pk_mul_f32 v[48:49], v[158:159], v[48:49]
	v_mov_b32_e32 v108, v22
	v_pk_mul_f32 v[50:51], v[50:51], v[48:49]
	v_pk_mul_f32 v[48:49], v[160:161], v[48:49]
	v_mov_b32_e32 v16, v21
	v_add_f32_e32 v22, v48, v49
	v_pk_mul_f32 v[48:49], v[4:5], v[100:101] op_sel_hi:[0,1]
	v_pk_mul_f32 v[16:17], v[16:17], v[48:49]
	v_mov_b32_e32 v24, v45
	v_mov_b32_e32 v44, v25
	v_pk_mul_f32 v[20:21], v[24:25], v[16:17]
	v_pk_mul_f32 v[16:17], v[44:45], v[16:17]
	v_mov_b32_e32 v109, v18
	v_add_f32_e32 v25, v16, v17
	v_pk_mul_f32 v[16:17], v[4:5], v[102:103] op_sel_hi:[0,1]
	v_mov_b32_e32 v110, v26
	v_mov_b32_e32 v111, v46
	v_sub_f32_e32 v24, v21, v20
	v_pk_mul_f32 v[16:17], v[16:17], v[108:109]
	v_mov_b32_e32 v20, v46
	v_mov_b32_e32 v21, v26
	v_pk_mul_f32 v[20:21], v[16:17], v[20:21]
	v_pk_mul_f32 v[16:17], v[16:17], v[110:111]
	v_sub_f32_e32 v20, v21, v20
	v_add_f32_e32 v21, v16, v17
	v_pk_mul_f32 v[16:17], v[4:5], v[112:113] op_sel_hi:[0,1]
	v_mov_b32_e32 v18, v23
	v_pk_mul_f32 v[16:17], v[16:17], v[18:19]
	v_mov_b32_e32 v26, v47
	v_mov_b32_e32 v46, v27
	v_pk_mul_f32 v[18:19], v[16:17], v[26:27]
	v_pk_mul_f32 v[16:17], v[16:17], v[46:47]
	v_mov_b32_e32 v76, v8
	v_add_f32_e32 v26, v16, v17
	v_pk_mul_f32 v[16:17], v[4:5], v[70:71] op_sel_hi:[0,1]
	v_mov_b32_e32 v77, v12
	v_sub_f32_e32 v23, v19, v18
	v_pk_mul_f32 v[16:17], v[16:17], v[74:75]
	v_mov_b32_e32 v18, v12
	v_mov_b32_e32 v19, v8
	v_pk_mul_f32 v[18:19], v[16:17], v[18:19]
	v_pk_mul_f32 v[16:17], v[16:17], v[76:77]
	v_sub_f32_e32 v18, v19, v18
	v_add_f32_e32 v19, v16, v17
	v_pk_mul_f32 v[16:17], v[4:5], v[78:79] op_sel_hi:[0,1]
	v_mov_b32_e32 v0, v5
	v_pk_mul_f32 v[0:1], v[16:17], v[0:1]
	v_mov_b32_e32 v8, v13
	v_pk_mul_f32 v[16:17], v[0:1], v[8:9]
	v_mov_b32_e32 v12, v9
	v_sub_f32_e32 v5, v17, v16
	v_pk_mul_f32 v[0:1], v[0:1], v[12:13]
	v_mov_b32_e32 v62, v6
	v_add_f32_e32 v12, v0, v1
	v_pk_mul_f32 v[0:1], v[4:5], v[58:59] op_sel_hi:[0,1]
	v_mov_b32_e32 v64, v10
	v_mov_b32_e32 v65, v14
	v_pk_mul_f32 v[0:1], v[0:1], v[62:63]
	v_mov_b32_e32 v8, v14
	v_mov_b32_e32 v9, v10
	v_pk_mul_f32 v[8:9], v[0:1], v[8:9]
	v_pk_mul_f32 v[0:1], v[0:1], v[64:65]
	v_sub_f32_e32 v8, v9, v8
	v_add_f32_e32 v9, v0, v1
	v_pk_mul_f32 v[0:1], v[4:5], v[66:67] op_sel_hi:[0,1]
	v_mov_b32_e32 v2, v7
	v_pk_mul_f32 v[0:1], v[0:1], v[2:3]
	v_mov_b32_e32 v10, v15
	v_mov_b32_e32 v14, v11
	v_pk_mul_f32 v[2:3], v[0:1], v[10:11]
	v_pk_mul_f32 v[0:1], v[0:1], v[14:15]
	v_sub_f32_e32 v6, v51, v50
	v_sub_f32_e32 v2, v3, v2
	v_add_f32_e32 v0, v0, v1
	v_cvt_pk_bf16_f32 v48, v6, v24
	v_cvt_pk_bf16_f32 v49, v20, v23
	v_cvt_pk_bf16_f32 v50, v18, v5
	v_cvt_pk_bf16_f32 v51, v8, v2
	v_cvt_pk_bf16_f32 v98, v22, v25
	v_cvt_pk_bf16_f32 v99, v21, v26
	v_cvt_pk_bf16_f32 v100, v19, v12
	v_cvt_pk_bf16_f32 v101, v9, v0
	global_load_dwordx4 v[0:3], v[150:151], off offset:80
	global_load_dwordx4 v[6:9], v[150:151], off offset:64
	global_load_dwordx4 v[10:13], v[150:151], off offset:208
	global_load_dwordx4 v[14:17], v[150:151], off offset:192
	v_pk_mul_f32 v[18:19], v[4:5], v[42:43] op_sel_hi:[0,1]
	s_waitcnt vmcnt(2)
	v_mov_b32_e32 v21, v6
	s_waitcnt vmcnt(0)
	v_mov_b32_e32 v20, v14
	v_pk_mul_f32 v[26:27], v[18:19], v[20:21]
	global_load_dwordx4 v[18:21], v119, s[82:83] offset:16
	global_load_dwordx4 v[22:25], v119, s[82:83]
	global_load_dwordx4 v[42:45], v119, s[92:93] offset:16
	global_load_dwordx4 v[52:55], v119, s[92:93]
	v_mov_b32_e32 v6, v15
	s_waitcnt vmcnt(2)
	v_mov_b32_e32 v47, v22
	s_waitcnt vmcnt(0)
	v_mov_b32_e32 v46, v52
	v_pk_mul_f32 v[46:47], v[26:27], v[46:47]
	s_nop 0
	v_sub_f32_e32 v5, v47, v46
	v_mov_b32_e32 v46, v22
	v_mov_b32_e32 v47, v52
	v_pk_mul_f32 v[26:27], v[26:27], v[46:47]
	v_mov_b32_e32 v22, v53
	v_add_f32_e32 v46, v26, v27
	v_pk_mul_f32 v[26:27], v[4:5], v[40:41] op_sel_hi:[0,1]
	v_pk_mul_f32 v[6:7], v[26:27], v[6:7]
	v_mov_b32_e32 v52, v23
	v_pk_mul_f32 v[14:15], v[6:7], v[22:23]
	v_pk_mul_f32 v[6:7], v[6:7], v[52:53]
	v_sub_f32_e32 v22, v15, v14
	v_add_f32_e32 v23, v6, v7
	v_pk_mul_f32 v[6:7], v[4:5], v[38:39] op_sel_hi:[0,1]
	v_mov_b32_e32 v14, v16
	v_mov_b32_e32 v15, v8
	v_pk_mul_f32 v[6:7], v[6:7], v[14:15]
	v_mov_b32_e32 v14, v54
	v_mov_b32_e32 v15, v24
	v_pk_mul_f32 v[14:15], v[6:7], v[14:15]
	v_mov_b32_e32 v8, v17
	v_sub_f32_e32 v16, v15, v14
	v_mov_b32_e32 v14, v24
	v_mov_b32_e32 v15, v54
	v_pk_mul_f32 v[6:7], v[6:7], v[14:15]
	v_mov_b32_e32 v24, v55
	v_add_f32_e32 v14, v6, v7
	v_pk_mul_f32 v[6:7], v[4:5], v[36:37] op_sel_hi:[0,1]
	v_pk_mul_f32 v[6:7], v[6:7], v[8:9]
	v_mov_b32_e32 v54, v25
	v_pk_mul_f32 v[8:9], v[6:7], v[24:25]
	v_pk_mul_f32 v[6:7], v[6:7], v[54:55]
	v_sub_f32_e32 v15, v9, v8
	v_add_f32_e32 v17, v6, v7
	v_pk_mul_f32 v[6:7], v[4:5], v[34:35] op_sel_hi:[0,1]
	v_mov_b32_e32 v8, v10
	v_mov_b32_e32 v9, v0
	v_pk_mul_f32 v[6:7], v[6:7], v[8:9]
	v_mov_b32_e32 v8, v42
	v_mov_b32_e32 v9, v18
	v_pk_mul_f32 v[8:9], v[6:7], v[8:9]
	v_mov_b32_e32 v0, v11
	v_sub_f32_e32 v10, v9, v8
	v_mov_b32_e32 v8, v18
	v_mov_b32_e32 v9, v42
	v_pk_mul_f32 v[6:7], v[6:7], v[8:9]
	v_mov_b32_e32 v18, v43
	v_add_f32_e32 v8, v6, v7
	v_pk_mul_f32 v[6:7], v[4:5], v[32:33] op_sel_hi:[0,1]
	v_pk_mul_f32 v[0:1], v[6:7], v[0:1]
	v_mov_b32_e32 v42, v19
	v_pk_mul_f32 v[6:7], v[0:1], v[18:19]
	v_pk_mul_f32 v[0:1], v[0:1], v[42:43]
	v_sub_f32_e32 v9, v7, v6
	v_add_f32_e32 v11, v0, v1
	v_pk_mul_f32 v[0:1], v[4:5], v[30:31] op_sel_hi:[0,1]
	v_mov_b32_e32 v6, v12
	v_mov_b32_e32 v7, v2
	v_pk_mul_f32 v[0:1], v[0:1], v[6:7]
	v_mov_b32_e32 v6, v44
	v_mov_b32_e32 v7, v20
	v_pk_mul_f32 v[6:7], v[0:1], v[6:7]
	v_mov_b32_e32 v2, v13
	v_sub_f32_e32 v12, v7, v6
	v_mov_b32_e32 v6, v20
	v_mov_b32_e32 v7, v44
	v_pk_mul_f32 v[0:1], v[0:1], v[6:7]
	v_mov_b32_e32 v20, v45
	v_add_f32_e32 v6, v0, v1
	v_pk_mul_f32 v[0:1], v[4:5], v[28:29] op_sel_hi:[0,1]
	v_pk_mul_f32 v[0:1], v[0:1], v[2:3]
	v_mov_b32_e32 v44, v21
	v_pk_mul_f32 v[2:3], v[0:1], v[20:21]
	v_pk_mul_f32 v[0:1], v[0:1], v[44:45]
	v_sub_f32_e32 v2, v3, v2
	v_add_f32_e32 v0, v0, v1
	v_cvt_pk_bf16_f32 v102, v5, v22
	v_cvt_pk_bf16_f32 v103, v16, v15
	v_cvt_pk_bf16_f32 v104, v10, v9
	v_cvt_pk_bf16_f32 v105, v12, v2
	v_cvt_pk_bf16_f32 v106, v46, v23
	v_cvt_pk_bf16_f32 v107, v14, v17
	v_cvt_pk_bf16_f32 v108, v8, v11
	v_cvt_pk_bf16_f32 v109, v6, v0
	ds_read_b128 v[0:3], v202
	ds_read_b128 v[4:7], v202 offset:32
	s_waitcnt lgkmcnt(1)
	v_mfma_f32_32x32x16_bf16 v[64:79], v[0:3], v[48:51], 0
	ds_read_b128 v[0:3], v202 offset:64
	s_waitcnt lgkmcnt(1)
	v_mfma_f32_32x32x16_bf16 v[64:79], v[4:7], v[102:105], v[64:79]
	s_waitcnt lgkmcnt(0)
	v_mfma_f32_32x32x16_bf16 v[64:79], v[0:3], v[98:101], v[64:79]
	ds_read_b128 v[0:3], v202 offset:96
	s_waitcnt lgkmcnt(0)
	v_mfma_f32_32x32x16_bf16 v[64:79], v[0:3], v[106:109], v[64:79]
	ds_read_b128 v[0:3], v203
	ds_read_b128 v[4:7], v203 offset:32
	s_waitcnt lgkmcnt(1)
	v_mfma_f32_32x32x16_bf16 v[32:47], v[0:3], v[48:51], 0
	ds_read_b128 v[0:3], v203 offset:64
	s_waitcnt lgkmcnt(1)
	v_mfma_f32_32x32x16_bf16 v[32:47], v[4:7], v[102:105], v[32:47]
	s_waitcnt lgkmcnt(0)
	v_mfma_f32_32x32x16_bf16 v[32:47], v[0:3], v[98:101], v[32:47]
	ds_read_b128 v[0:3], v203 offset:96
	s_waitcnt lgkmcnt(0)
	v_mfma_f32_32x32x16_bf16 v[32:47], v[0:3], v[106:109], v[32:47]
	ds_read_b128 v[0:3], v204
	ds_read_b128 v[4:7], v204 offset:32
	s_waitcnt lgkmcnt(1)
	v_mfma_f32_32x32x16_bf16 v[16:31], v[0:3], v[48:51], 0
	ds_read_b128 v[0:3], v204 offset:64
	s_waitcnt lgkmcnt(1)
	v_mfma_f32_32x32x16_bf16 v[16:31], v[4:7], v[102:105], v[16:31]
	s_waitcnt lgkmcnt(0)
	v_mfma_f32_32x32x16_bf16 v[16:31], v[0:3], v[98:101], v[16:31]
	ds_read_b128 v[0:3], v204 offset:96
	s_waitcnt lgkmcnt(0)
	v_mfma_f32_32x32x16_bf16 v[16:31], v[0:3], v[106:109], v[16:31]
	ds_read_b128 v[0:3], v205
	ds_read_b128 v[52:55], v205 offset:32
	s_waitcnt lgkmcnt(1)
	v_mfma_f32_32x32x16_bf16 v[0:15], v[0:3], v[48:51], 0
	s_waitcnt lgkmcnt(0)
	v_mfma_f32_32x32x16_bf16 v[0:15], v[52:55], v[102:105], v[0:15]
	ds_read_b128 v[52:55], v205 offset:64
	s_waitcnt lgkmcnt(0)
	v_mfma_f32_32x32x16_bf16 v[0:15], v[52:55], v[98:101], v[0:15]
	ds_read_b128 v[52:55], v205 offset:96
	s_waitcnt lgkmcnt(0)
	v_mfma_f32_32x32x16_bf16 v[0:15], v[52:55], v[106:109], v[0:15]
	ds_read_b128 v[52:55], v206
	ds_read_b128 v[110:113], v206 offset:32
	s_waitcnt lgkmcnt(1)
	v_mfma_f32_32x32x16_bf16 v[48:63], v[52:55], v[48:51], 0
	s_waitcnt lgkmcnt(0)
	v_mfma_f32_32x32x16_bf16 v[48:63], v[110:113], v[102:105], v[48:63]
	ds_read_b128 v[102:105], v206 offset:64
	s_waitcnt lgkmcnt(0)
	v_mfma_f32_32x32x16_bf16 v[48:63], v[102:105], v[98:101], v[48:63]
	ds_read_b128 v[98:101], v206 offset:96
	s_waitcnt lgkmcnt(0)
	v_mfma_f32_32x32x16_bf16 v[48:63], v[98:101], v[106:109], v[48:63]
	s_cbranch_vccz .LBB0_346
	v_cndmask_b32_e64 v98, v212, v64, s[2:3]
	v_cndmask_b32_e64 v105, v65, v212, s[4:5]
	v_cndmask_b32_e64 v104, v212, v66, s[6:7]
	v_cndmask_b32_e64 v103, v212, v67, s[8:9]
	v_cndmask_b32_e64 v102, v212, v68, s[10:11]
	v_cndmask_b32_e64 v101, v212, v69, s[12:13]
	v_cndmask_b32_e64 v100, v212, v70, s[14:15]
	v_cndmask_b32_e64 v99, v212, v71, s[16:17]
	v_cndmask_b32_e64 v71, v212, v72, s[18:19]
	v_cndmask_b32_e64 v70, v212, v73, s[20:21]
	v_cndmask_b32_e64 v69, v212, v74, s[22:23]
	v_cndmask_b32_e64 v68, v212, v75, s[24:25]
	v_cndmask_b32_e64 v67, v212, v76, s[26:27]
	v_cndmask_b32_e64 v66, v212, v77, s[28:29]
	v_cndmask_b32_e64 v65, v212, v78, s[30:31]
	v_cndmask_b32_e64 v64, v212, v79, s[34:35]
	s_branch .LBB0_347
